# DA K tile row stride 272->288 B (bank-conflict-free ds_read_b128 for the QK fragments), K buffers 18 KB each
# speedup vs baseline: 1.0074x; 1.0004x over previous
; __device__ __forceinline__ uint2 pack4(float a, float b, float c, float d) { uint2 r; r.x = pk2(a, b); r.y = pk2(c, d); return r; }
; template <int NC, int DQK, int DV, bool CAUSAL, bool PF> ...
;     ...
;         _Pragma("unroll") for (int m = 0; m < 4; ++m) _Pragma("unroll") for (int j = 0; j < 4; ++j) { float pv = __builtin_amdgcn_exp2f(s[m][j] - mm); s[m][j] = pv; psum += pv; }
;       } else {
;         float cc = bb - mrun[c];
;         _Pragma("unroll") for (int m = 0; m < 4; ++m) _Pragma("unroll") for (int j = 0; j < 4; ++j) { float pv = __builtin_amdgcn_exp2f(s[m][j] * scale_log2 + cc); s[m][j] = pv; psum += pv; }
;       }
;       lsum[c] += psum;
;       _Pragma("unroll") for (int k2 = 0; k2 < 2; ++k2) {
;         uint2 lo = pack4(s[2 * k2][0], s[2 * k2][1], s[2 * k2][2], s[2 * k2][3]);
;         uint2 hi = pack4(s[2 * k2 + 1][0], s[2 * k2 + 1][1], s[2 * k2 + 1][2], s[2 * k2 + 1][3]);
;         uint4 pk; pk.x = lo.x; pk.y = lo.y; pk.z = hi.x; pk.w = hi.y;
;         pf[c][k2] = *(bf16x8*)&pk;
;       }
;     }
;     _Pragma("unroll") for (int k2 = 0; k2 < 2; ++k2) _Pragma("unroll") for (int v = 0; v < NVT; ++v) {
;       bf16x8 a = *(const bf16x8*)&Vb[(16 * v + fr) * VLD + 32 * k2 + fq * 8];
;       _Pragma("unroll") for (int c = 0; c < NC; ++c) O[c][v] = __builtin_amdgcn_mfma_f32_16x16x32_bf16(a, pf[c][k2], O[c][v], 0, 0, 0);
;       if ((v & 3) == 3) __builtin_amdgcn_sched_barrier(0);
;     }
.LBB0_1776:
	s_or_b64 exec, exec, s[6:7]
	v_exp_f32_e32 v15, v147
	v_cvt_pk_bf16_f32 v117, v6, v7
	v_exp_f32_e32 v7, v123
	v_add3_u32 v32, s31, v32, v193
	v_add_f32_e32 v31, v15, v146
	v_add_f32_e32 v192, v192, v31
	v_cvt_pk_bf16_f32 v116, v4, v5
	v_add_f32_e32 v4, v7, v122
	v_cvt_pk_bf16_f32 v6, v28, v29
	v_cvt_pk_bf16_f32 v7, v30, v7
	ds_read_b128 v[28:31], v32 offset:41984
	v_cvt_pk_bf16_f32 v114, v0, v1
	v_cvt_pk_bf16_f32 v115, v2, v3
	v_cvt_pk_bf16_f32 v0, v8, v9
	v_cvt_pk_bf16_f32 v1, v10, v11
	v_cvt_pk_bf16_f32 v8, v16, v17
	v_cvt_pk_bf16_f32 v9, v18, v19
	v_cvt_pk_bf16_f32 v10, v20, v21
	v_cvt_pk_bf16_f32 v11, v22, v23
	s_waitcnt lgkmcnt(0)
	v_mfma_f32_16x16x32_bf16 v[90:93], v[28:31], v[114:117], v[90:93]
	v_cvt_pk_bf16_f32 v2, v12, v13
	v_cvt_pk_bf16_f32 v3, v14, v15
	ds_read_b128 v[12:15], v32 offset:36864
	ds_read_b128 v[20:23], v32 offset:39424
	v_mfma_f32_16x16x32_bf16 v[28:31], v[28:31], v[8:11], v[94:97]
	v_add_f32_e32 v191, v191, v4
	v_cvt_pk_bf16_f32 v4, v24, v25
	v_cvt_pk_bf16_f32 v5, v26, v27
	ds_read_b128 v[94:97], v32 offset:44544
	s_waitcnt lgkmcnt(0)
	v_mfma_f32_16x16x32_bf16 v[78:81], v[94:97], v[114:117], v[78:81]
	v_mfma_f32_16x16x32_bf16 v[74:77], v[94:97], v[8:11], v[74:77]
	v_mfma_f32_16x16x32_bf16 v[16:19], v[12:15], v[114:117], v[106:109]
	v_mfma_f32_16x16x32_bf16 v[12:15], v[12:15], v[8:11], v[110:113]
	v_mfma_f32_16x16x32_bf16 v[24:27], v[20:23], v[114:117], v[98:101]
	v_mfma_f32_16x16x32_bf16 v[20:23], v[20:23], v[8:11], v[102:105]
	ds_read_b128 v[94:97], v32 offset:47104
	s_waitcnt lgkmcnt(0)
	v_mfma_f32_16x16x32_bf16 v[62:65], v[94:97], v[114:117], v[62:65]
	v_mfma_f32_16x16x32_bf16 v[70:73], v[94:97], v[8:11], v[70:73]
	ds_read_b128 v[94:97], v32 offset:49664
	s_waitcnt lgkmcnt(0)
	v_mfma_f32_16x16x32_bf16 v[50:53], v[94:97], v[114:117], v[50:53]
	v_mfma_f32_16x16x32_bf16 v[66:69], v[94:97], v[8:11], v[66:69]
	ds_read_b128 v[94:97], v32 offset:52224
	s_waitcnt lgkmcnt(0)
	v_mfma_f32_16x16x32_bf16 v[54:57], v[94:97], v[114:117], v[54:57]
	v_mfma_f32_16x16x32_bf16 v[58:61], v[94:97], v[8:11], v[58:61]
	ds_read_b128 v[94:97], v32 offset:54784
	s_waitcnt lgkmcnt(0)
	v_mfma_f32_16x16x32_bf16 v[82:85], v[94:97], v[114:117], v[82:85]
	v_mfma_f32_16x16x32_bf16 v[8:11], v[94:97], v[8:11], v[86:89]
	s_nop 2
	ds_read_b128 v[86:89], v32 offset:36928
	s_waitcnt lgkmcnt(0)
	v_mfma_f32_16x16x32_bf16 v[110:113], v[86:89], v[4:7], v[12:15]
	s_nop 2
	ds_read_b128 v[12:15], v32 offset:39488
	v_mfma_f32_16x16x32_bf16 v[106:109], v[86:89], v[0:3], v[16:19]
	s_waitcnt lgkmcnt(0)
	v_mfma_f32_16x16x32_bf16 v[98:101], v[12:15], v[0:3], v[24:27]
	v_mfma_f32_16x16x32_bf16 v[102:105], v[12:15], v[4:7], v[20:23]
	ds_read_b128 v[12:15], v32 offset:42048
	s_waitcnt lgkmcnt(0)
	v_mfma_f32_16x16x32_bf16 v[90:93], v[12:15], v[0:3], v[90:93]
	v_mfma_f32_16x16x32_bf16 v[94:97], v[12:15], v[4:7], v[28:31]
	ds_read_b128 v[12:15], v32 offset:44608
	s_waitcnt lgkmcnt(0)
	v_mfma_f32_16x16x32_bf16 v[78:81], v[12:15], v[0:3], v[78:81]
	v_mfma_f32_16x16x32_bf16 v[74:77], v[12:15], v[4:7], v[74:77]
	ds_read_b128 v[12:15], v32 offset:47168
	s_waitcnt lgkmcnt(0)
	v_mfma_f32_16x16x32_bf16 v[62:65], v[12:15], v[0:3], v[62:65]
	v_mfma_f32_16x16x32_bf16 v[70:73], v[12:15], v[4:7], v[70:73]
	ds_read_b128 v[12:15], v32 offset:49728
	s_waitcnt lgkmcnt(0)
	v_mfma_f32_16x16x32_bf16 v[50:53], v[12:15], v[0:3], v[50:53]
	v_mfma_f32_16x16x32_bf16 v[66:69], v[12:15], v[4:7], v[66:69]
	ds_read_b128 v[12:15], v32 offset:52288
	s_waitcnt lgkmcnt(0)
	v_mfma_f32_16x16x32_bf16 v[54:57], v[12:15], v[0:3], v[54:57]
	v_mfma_f32_16x16x32_bf16 v[58:61], v[12:15], v[4:7], v[58:61]
	ds_read_b128 v[12:15], v32 offset:54848
	s_waitcnt lgkmcnt(0)
	v_mfma_f32_16x16x32_bf16 v[82:85], v[12:15], v[0:3], v[82:85]
	v_mfma_f32_16x16x32_bf16 v[86:89], v[12:15], v[4:7], v[8:11]

; template <int NC, int DQK, int DV, bool CAUSAL, bool PF> ...
;     ...
;   int tid = opaque_tid(wv), wid = tid >> 6, lane = tid & 63, fr = lane & 15, fq = lane >> 4;
;   int qw0 = q0 + wid * 16, qpos = qw0 + fr;
;   bf16x8 qf[NC][NKS];
;   _Pragma("unroll") for (int c = 0; c < NC; ++c) _Pragma("unroll") for (int ks = 0; ks < NKS; ++ks)
;     qf[c][ks] = *(const bf16x8*)&Qg[(long)(wid * 16 + fr) * q_stride + c * DQK + ks * 32 + fq * 8];
;   f32x4 O[NC][NVT];
;   _Pragma("unroll") for (int c = 0; c < NC; ++c) _Pragma("unroll") for (int v = 0; v < NVT; ++v) O[c][v] = f32x4{0.f, 0.f, 0.f, 0.f};
;   float mrun[NC], lsum[NC];
;   _Pragma("unroll") for (int c = 0; c < NC; ++c) { mrun[c] = -1e30f; lsum[c] = 0.f; }
;   const __amdgpu_buffer_rsrc_t rsK = __builtin_amdgcn_make_buffer_rsrc((void*)Kg, 0, 0x7fffffff, 0x00020000);
;   const __amdgpu_buffer_rsrc_t rsV = __builtin_amdgcn_make_buffer_rsrc((void*)VTg, 0, 0x7fffffff, 0x00020000);
;   const __amdgpu_buffer_rsrc_t rsNK = __builtin_amdgcn_make_buffer_rsrc((void*)nKg, 0, 0x7fffffff, 0x00020000);
;   const __amdgpu_buffer_rsrc_t rsNV = __builtin_amdgcn_make_buffer_rsrc((void*)nVTg, 0, 0x7fffffff, 0x00020000);
;   int kvo[KPT], vvo[VPT];
;   _Pragma("unroll") for (int i = 0; i < KPT; ++i) { int id = tid + i * 512, row = id / KCH, cc = id % KCH; kvo[i] = (row * k_stride + cc * 8) * 2; }
;   _Pragma("unroll") for (int i = 0; i < VPT; ++i) { int id = tid + i * 512, row = id >> 3, cc = id & 7; vvo[i] = (row * vt_stride + cc * 8) * 2; }
;     ...
;   if (PF && !pre0) FA_PREFETCH(0);
;   for (int kt = 0; kt < nkt; ++kt) {
;     if (!PF) FA_PREFETCH(kt);
;     u16* Kb = Ks + (kt & 1) * KBUF; u16* Vb = Vs + (kt & 1) * VBUF;
;     _Pragma("unroll") for (int i = 0; i < KPT; ++i) { int id = tid + i * 512, row = id / KCH, cc = id % KCH; *(u32x4*)&Kb[row * KLD + cc * 8] = kreg[i]; }
;     ...
;         _Pragma("unroll") for (int m = 0; m < 4; ++m) _Pragma("unroll") for (int j = 0; j < 4; ++j) { float pv = __builtin_amdgcn_exp2f(s[m][j] - mm); s[m][j] = pv; psum += pv; }
;       } else {
;         float cc = bb - mrun[c];
;         _Pragma("unroll") for (int m = 0; m < 4; ++m) _Pragma("unroll") for (int j = 0; j < 4; ++j) { float pv = __builtin_amdgcn_exp2f(s[m][j] * scale_log2 + cc); s[m][j] = pv; psum += pv; }
;       }
;       lsum[c] += psum;
;       _Pragma("unroll") for (int k2 = 0; k2 < 2; ++k2) {
.LBB0_1782:
	s_lshl_b64 s[18:19], s[0:1], 10
	v_and_b32_e32 v6, 63, v0
	v_and_b32_e32 v196, 15, v0
	v_bfe_u32 v7, v0, 4, 2
	v_and_b32_e32 v206, 32, v5
	v_lshlrev_b32_e32 v5, 4, v0
	v_lshlrev_b32_e32 v8, 1, v0
	v_lshrrev_b32_e32 v0, 3, v0
	s_movk_i32 s0, 0xa0
	v_mul_lo_u32 v208, v0, s0
	v_lshrrev_b32_e32 v0, 3, v3
	v_and_b32_e32 v1, -16, v1
	v_mul_lo_u32 v207, v0, s0
	s_sub_i32 s0, s8, 51
	v_mov_b32_e32 v52, v33
	v_mov_b32_e32 v53, v33
	s_lshr_b32 s30, s8, 6
	v_add_u32_e32 v197, s8, v1
	v_and_b32_e32 v5, 16, v5
	v_and_b32_e32 v8, 4, v8
	v_lshlrev_b32_e32 v6, 2, v6
	v_lshlrev_b32_e32 v190, 2, v7
	v_add3_u32 v0, s0, v1, v196
	v_mov_b32_e32 v50, v33
	v_mov_b32_e32 v51, v33
	v_mov_b64_e32 v[64:65], v[52:53]
	v_mov_b64_e32 v[80:81], v[52:53]
	v_mov_b64_e32 v[92:93], v[52:53]
	v_mov_b64_e32 v[100:101], v[52:53]
	v_mov_b64_e32 v[108:109], v[52:53]
	v_mov_b64_e32 v[56:57], v[52:53]
	v_mov_b64_e32 v[84:85], v[52:53]
	v_mov_b64_e32 v[112:113], v[52:53]
	v_mov_b64_e32 v[104:105], v[52:53]
	v_mov_b64_e32 v[96:97], v[52:53]
	v_mov_b64_e32 v[76:77], v[52:53]
	v_mov_b64_e32 v[72:73], v[52:53]
	v_mov_b64_e32 v[68:69], v[52:53]
	v_mov_b64_e32 v[60:61], v[52:53]
	v_mov_b64_e32 v[88:89], v[52:53]
	v_or_b32_e32 v203, 15, v197
	v_add_u32_e32 v202, 0xffffff8f, v197
	s_movk_i32 s31, 0x80
	v_xor_b32_e32 v189, 0x80, v6
	v_mul_u32_u24_e32 v210, 0x120, v2
	v_mul_u32_u24_e32 v209, 0x120, v4
	v_mul_u32_u24_e32 v195, 0x120, v196
	v_mul_u32_u24_e32 v193, 0xa0, v196
	s_add_i32 s30, s30, 1
	v_sub_u32_e32 v213, v0, v190
	s_mov_b32 s34, 0
	v_mov_b32_e32 v191, 0
	v_mov_b32_e32 v171, 0xf149f2ca
	s_mov_b32 s35, 63
	s_mov_b32 s36, 0x20000
	v_lshlrev_b32_e32 v211, 1, v5
	v_lshlrev_b32_e32 v212, 1, v8
	v_mov_b64_e32 v[62:63], v[50:51]
	v_mov_b64_e32 v[78:79], v[50:51]
	v_mov_b64_e32 v[90:91], v[50:51]
	v_mov_b64_e32 v[98:99], v[50:51]
	v_mov_b64_e32 v[106:107], v[50:51]
	v_mov_b32_e32 v194, 0xf149f2ca
	v_mov_b32_e32 v192, 0
	v_mov_b64_e32 v[54:55], v[50:51]
	v_mov_b64_e32 v[82:83], v[50:51]
	v_mov_b64_e32 v[110:111], v[50:51]
	v_mov_b64_e32 v[102:103], v[50:51]
	v_mov_b64_e32 v[94:95], v[50:51]
	v_mov_b64_e32 v[74:75], v[50:51]
	v_mov_b64_e32 v[70:71], v[50:51]
	v_mov_b64_e32 v[66:67], v[50:51]
	v_mov_b64_e32 v[58:59], v[50:51]
	v_mov_b64_e32 v[86:87], v[50:51]
	s_branch .LBB0_1785
.LBB0_1783:
	s_or_b64 exec, exec, s[6:7]
	v_exp_f32_e32 v15, v173
	v_cvt_pk_bf16_f32 v149, v6, v7
	v_exp_f32_e32 v7, v175
	v_add3_u32 v150, s37, v32, v193
	v_add_f32_e32 v31, v15, v172
	v_add_f32_e32 v192, v192, v31
	v_cvt_pk_bf16_f32 v148, v4, v5
	v_add_f32_e32 v4, v7, v174
	v_cvt_pk_bf16_f32 v6, v28, v29
	v_cvt_pk_bf16_f32 v7, v30, v7
	ds_read_b128 v[28:31], v150 offset:41984
	v_cvt_pk_bf16_f32 v146, v0, v1
	v_cvt_pk_bf16_f32 v147, v2, v3
	v_cvt_pk_bf16_f32 v0, v8, v9
	v_cvt_pk_bf16_f32 v1, v10, v11
	v_cvt_pk_bf16_f32 v8, v16, v17
	v_cvt_pk_bf16_f32 v9, v18, v19
	v_cvt_pk_bf16_f32 v10, v20, v21
	v_cvt_pk_bf16_f32 v11, v22, v23
	s_waitcnt lgkmcnt(0)
	v_mfma_f32_16x16x32_bf16 v[90:93], v[28:31], v[146:149], v[90:93]
	v_cvt_pk_bf16_f32 v2, v12, v13
	v_cvt_pk_bf16_f32 v3, v14, v15
	ds_read_b128 v[12:15], v150 offset:36864
	ds_read_b128 v[20:23], v150 offset:39424
	v_mfma_f32_16x16x32_bf16 v[28:31], v[28:31], v[8:11], v[94:97]
	v_add_f32_e32 v191, v191, v4
	v_cvt_pk_bf16_f32 v4, v24, v25
	v_cvt_pk_bf16_f32 v5, v26, v27
	ds_read_b128 v[94:97], v150 offset:44544
	s_waitcnt lgkmcnt(0)
	v_mfma_f32_16x16x32_bf16 v[78:81], v[94:97], v[146:149], v[78:81]
	v_mfma_f32_16x16x32_bf16 v[74:77], v[94:97], v[8:11], v[74:77]
	v_mfma_f32_16x16x32_bf16 v[16:19], v[12:15], v[146:149], v[106:109]
	v_mfma_f32_16x16x32_bf16 v[12:15], v[12:15], v[8:11], v[110:113]
	v_mfma_f32_16x16x32_bf16 v[24:27], v[20:23], v[146:149], v[98:101]
	v_mfma_f32_16x16x32_bf16 v[20:23], v[20:23], v[8:11], v[102:105]
	ds_read_b128 v[94:97], v150 offset:47104
	s_waitcnt lgkmcnt(0)
	v_mfma_f32_16x16x32_bf16 v[62:65], v[94:97], v[146:149], v[62:65]
	v_mfma_f32_16x16x32_bf16 v[70:73], v[94:97], v[8:11], v[70:73]
	ds_read_b128 v[94:97], v150 offset:49664
	s_waitcnt lgkmcnt(0)
	v_mfma_f32_16x16x32_bf16 v[50:53], v[94:97], v[146:149], v[50:53]
	v_mfma_f32_16x16x32_bf16 v[66:69], v[94:97], v[8:11], v[66:69]
	ds_read_b128 v[94:97], v150 offset:52224
	s_waitcnt lgkmcnt(0)
	v_mfma_f32_16x16x32_bf16 v[54:57], v[94:97], v[146:149], v[54:57]
	v_mfma_f32_16x16x32_bf16 v[58:61], v[94:97], v[8:11], v[58:61]
	ds_read_b128 v[94:97], v150 offset:54784
	s_waitcnt lgkmcnt(0)
	v_mfma_f32_16x16x32_bf16 v[82:85], v[94:97], v[146:149], v[82:85]
	v_mfma_f32_16x16x32_bf16 v[8:11], v[94:97], v[8:11], v[86:89]
	s_nop 2
	ds_read_b128 v[86:89], v150 offset:36928
	s_waitcnt lgkmcnt(0)
	v_mfma_f32_16x16x32_bf16 v[110:113], v[86:89], v[4:7], v[12:15]
	s_nop 2
	ds_read_b128 v[12:15], v150 offset:39488
	v_mfma_f32_16x16x32_bf16 v[106:109], v[86:89], v[0:3], v[16:19]
	s_waitcnt lgkmcnt(0)
	v_mfma_f32_16x16x32_bf16 v[98:101], v[12:15], v[0:3], v[24:27]
	v_mfma_f32_16x16x32_bf16 v[102:105], v[12:15], v[4:7], v[20:23]
	ds_read_b128 v[12:15], v150 offset:42048
	s_waitcnt lgkmcnt(0)
	v_mfma_f32_16x16x32_bf16 v[90:93], v[12:15], v[0:3], v[90:93]
	v_mfma_f32_16x16x32_bf16 v[94:97], v[12:15], v[4:7], v[28:31]
	ds_read_b128 v[12:15], v150 offset:44608
	s_waitcnt lgkmcnt(0)
	v_mfma_f32_16x16x32_bf16 v[78:81], v[12:15], v[0:3], v[78:81]
	v_mfma_f32_16x16x32_bf16 v[74:77], v[12:15], v[4:7], v[74:77]
	ds_read_b128 v[12:15], v150 offset:47168
	s_waitcnt lgkmcnt(0)
	v_mfma_f32_16x16x32_bf16 v[62:65], v[12:15], v[0:3], v[62:65]
	v_mfma_f32_16x16x32_bf16 v[70:73], v[12:15], v[4:7], v[70:73]
	ds_read_b128 v[12:15], v150 offset:49728
	s_waitcnt lgkmcnt(0)
	v_mfma_f32_16x16x32_bf16 v[50:53], v[12:15], v[0:3], v[50:53]
	v_mfma_f32_16x16x32_bf16 v[66:69], v[12:15], v[4:7], v[66:69]
	ds_read_b128 v[12:15], v150 offset:52288
	s_waitcnt lgkmcnt(0)
	v_mfma_f32_16x16x32_bf16 v[54:57], v[12:15], v[0:3], v[54:57]
	v_mfma_f32_16x16x32_bf16 v[58:61], v[12:15], v[4:7], v[58:61]
	ds_read_b128 v[12:15], v150 offset:54848
	s_waitcnt lgkmcnt(0)
	v_mfma_f32_16x16x32_bf16 v[82:85], v[12:15], v[0:3], v[82:85]
	v_mfma_f32_16x16x32_bf16 v[86:89], v[12:15], v[4:7], v[8:11]

; #define FA_PREFETCH(kt_) do { int k0_ = (kt_) * 64; \
;     _Pragma("unroll") for (int i = 0; i < KPT; ++i) kreg[i] = __builtin_amdgcn_raw_buffer_load_b128(rsK, kvo[i], k0_ * k_stride * 2, 0); \
;     _Pragma("unroll") for (int i = 0; i < VPT; ++i) vreg[i] = __builtin_amdgcn_raw_buffer_load_b128(rsV, vvo[i], k0_ * 2, 0); } while (0)
; #define FA_PREFETCH_NEXT() do { \
;     _Pragma("unroll") for (int i = 0; i < KPT; ++i) kreg[i] = __builtin_amdgcn_raw_buffer_load_b128(rsNK, kvo[i], 0, 0); \
;     _Pragma("unroll") for (int i = 0; i < VPT; ++i) vreg[i] = __builtin_amdgcn_raw_buffer_load_b128(rsNV, vvo[i], 0, 0); } while (0)
; template <int NC, int DQK, int DV, bool CAUSAL, bool PF> ...
;     ...
;   for (int kt = 0; kt < nkt; ++kt) {
;     if (!PF) FA_PREFETCH(kt);
;     u16* Kb = Ks + (kt & 1) * KBUF; u16* Vb = Vs + (kt & 1) * VBUF;
;     _Pragma("unroll") for (int i = 0; i < KPT; ++i) { int id = tid + i * 512, row = id / KCH, cc = id % KCH; *(u32x4*)&Kb[row * KLD + cc * 8] = kreg[i]; }
;     _Pragma("unroll") for (int i = 0; i < VPT; ++i) {
;       int id = tid + i * 512, row = id >> 3, cc = id & 7;
;       int pos = 32 * (cc >> 2) + 16 * (cc & 1) + 4 * ((cc >> 1) & 1);
;       uint2 lo2, hi2; lo2.x = vreg[i][0]; lo2.y = vreg[i][1]; hi2.x = vreg[i][2]; hi2.y = vreg[i][3];
;       *(uint2*)&Vb[row * VLD + pos] = lo2; *(uint2*)&Vb[row * VLD + pos + 8] = hi2;
;     }
;     __syncthreads();
;     if (PF && kt + 1 < nkt) FA_PREFETCH(kt + 1); else if (PF && has_next_item) FA_PREFETCH_NEXT();
;     int k0 = kt * 64;
;     if (CAUSAL && k0 > qw0 + 15) continue;
;     bf16x8 pf[NC][2];
;     bool general = false; float bb = 0.f;
;     if (CAUSAL) { general = (qw0 - (k0 + 63)) < 113; bb = btab[127]; }
;     f32x4 bv[4];
;     if (general) {
;       bool diag = (k0 + 63) > qw0;
.LBB0_1785:
	s_and_b32 s0, s34, 1
	s_mul_i32 s1, s0, 0x4800
	s_add_i32 s38, s1, 0
	v_add3_u32 v0, s38, v210, v204
	s_mul_hi_u32 s0, s34, 0xaaaaaaab
	s_lshr_b32 s0, s0, 1
	s_mul_i32 s0, s0, 3
	s_sub_i32 s0, s34, s0
	s_mul_i32 s0, s0, 0x5000
	s_waitcnt vmcnt(3)
	ds_write_b128 v0, v[34:37]
	v_add3_u32 v0, s38, v209, v205
	s_mov_b32 s37, s0
	s_waitcnt vmcnt(2)
	ds_write_b128 v0, v[38:41]
	v_lshl_add_u32 v0, v206, 1, s37
	v_add3_u32 v0, v0, v211, v212
	v_add_u32_e32 v1, v0, v208
	v_add_u32_e32 v0, v0, v207
	v_add_u32_e32 v1, 0x9000, v1
	v_add_u32_e32 v0, 0x9000, v0
	s_mov_b32 s14, s78
	s_mov_b32 s15, s79
	s_waitcnt vmcnt(0)
	ds_write2_b64 v1, v[42:43], v[44:45] offset1:2
	s_waitcnt vmcnt(0)
	ds_write2_b64 v0, v[46:47], v[48:49] offset1:2
	s_waitcnt lgkmcnt(0)
	s_barrier
	buffer_load_dwordx4 v[34:37], v198, s[76:79], s36 offen
	buffer_load_dwordx4 v[38:41], v199, s[76:79], s36 offen
	buffer_load_dwordx4 v[46:49], v200, s[12:15], s31 offen
	buffer_load_dwordx4 v[42:45], v201, s[12:15], s31 offen
	s_sub_i32 s0, s35, 63
	v_cmp_le_i32_e32 vcc, s0, v203
	s_and_saveexec_b64 s[0:1], vcc
	s_cbranch_execz .LBB0_1784
	v_readlane_b32 s6, v254, 39
	v_cmp_gt_i32_e32 vcc, s35, v202
	s_nop 0
	v_mov_b32_e32 v0, s6
	ds_read_b32 v170, v0
	v_cmp_le_i32_e64 s[6:7], s35, v202
	s_cbranch_vccz .Lda_fast_sel
	s_cmp_lt_u32 s97, 0x100
	s_cbranch_scc1 .Lda_gen_cont
	s_cmp_eq_u32 s34, 0
	s_cbranch_scc1 .Lda_gen_cont
	s_sub_i32 s8, s35, 64
	v_cmp_le_i32_e32 vcc, s8, v202
	s_cbranch_vccnz .Ldb_flushB
	v_cmp_gt_i32_e32 vcc, s35, v202

; template <int NC, int DQK, int DV, bool CAUSAL, bool PF> ...
;     ...
;       _Pragma("unroll") for (int ks = 0; ks < NKS; ++ks) _Pragma("unroll") for (int m = 0; m < 4; ++m) {
;         bf16x8 a = *(const bf16x8*)&Kb[(16 * m + fr) * KLD + c * DQK + ks * 32 + fq * 8];
;         s[m] = __builtin_amdgcn_mfma_f32_16x16x32_bf16(a, qf[c][ks], s[m], 0, 0, 0);
;       }
.Ldg_nomask:
.LBB0_1788:
	s_or_b64 exec, exec, s[14:15]
	v_add_u32_e32 v0, s38, v32
	v_add_u32_e32 v146, v0, v195
	ds_read_b128 v[0:3], v146
	ds_read_b128 v[16:19], v146 offset:64
	ds_read_b128 v[4:7], v146 offset:4608
	ds_read_b128 v[8:11], v146 offset:9216
	ds_read_b128 v[12:15], v146 offset:13824
	s_waitcnt lgkmcnt(4)
	v_mfma_f32_16x16x32_bf16 v[0:3], v[0:3], v[138:141], 0
	s_waitcnt lgkmcnt(3)
	v_mfma_f32_16x16x32_bf16 v[28:31], v[16:19], v[134:137], v[0:3]
	s_nop 5
	ds_read_b128 v[0:3], v146 offset:4672
	s_waitcnt lgkmcnt(3)
	v_mfma_f32_16x16x32_bf16 v[4:7], v[4:7], v[138:141], 0
	s_waitcnt lgkmcnt(0)
	v_mfma_f32_16x16x32_bf16 v[24:27], v[0:3], v[134:137], v[4:7]
	ds_read_b128 v[0:3], v146 offset:9280
	v_mfma_f32_16x16x32_bf16 v[8:11], v[8:11], v[138:141], 0
	s_waitcnt lgkmcnt(0)
	v_mfma_f32_16x16x32_bf16 v[20:23], v[0:3], v[134:137], v[8:11]
	ds_read_b128 v[0:3], v146 offset:13888
	v_mfma_f32_16x16x32_bf16 v[12:15], v[12:15], v[138:141], 0
	s_waitcnt lgkmcnt(0)
	v_mfma_f32_16x16x32_bf16 v[16:19], v[0:3], v[134:137], v[12:15]
	s_and_saveexec_b64 s[8:9], s[6:7]
	s_xor_b64 s[8:9], exec, s[8:9]
	s_cbranch_execnz .LBB0_1804
	s_andn2_saveexec_b64 s[8:9], s[8:9]
	s_cbranch_execnz .LBB0_1805

; template <int NC, int DQK, int DV, bool CAUSAL, bool PF> ...
;     ...
;     _Pragma("unroll") for (int c = 0; c < NC; ++c) {
;       f32x4 s[4];
;       _Pragma("unroll") for (int m = 0; m < 4; ++m) s[m] = f32x4{0.f, 0.f, 0.f, 0.f};
;       _Pragma("unroll") for (int ks = 0; ks < NKS; ++ks) _Pragma("unroll") for (int m = 0; m < 4; ++m) {
;         bf16x8 a = *(const bf16x8*)&Kb[(16 * m + fr) * KLD + c * DQK + ks * 32 + fq * 8];
;         s[m] = __builtin_amdgcn_mfma_f32_16x16x32_bf16(a, qf[c][ks], s[m], 0, 0, 0);
;       }
.LBB0_1796:
	s_or_b64 exec, exec, s[8:9]
	ds_read_b128 v[16:19], v146 offset:128
	ds_read_b128 v[148:151], v146 offset:192
	ds_read_b128 v[20:23], v146 offset:4736
	ds_read_b128 v[24:27], v146 offset:9344
	ds_read_b128 v[28:31], v146 offset:13952
	s_waitcnt lgkmcnt(4)
	v_mfma_f32_16x16x32_bf16 v[16:19], v[16:19], v[118:121], 0
	s_waitcnt lgkmcnt(3)
	v_mfma_f32_16x16x32_bf16 v[158:161], v[148:151], v[114:117], v[16:19]
	s_nop 5
	ds_read_b128 v[16:19], v146 offset:4800
	s_waitcnt lgkmcnt(3)
	v_mfma_f32_16x16x32_bf16 v[20:23], v[20:23], v[118:121], 0
	s_waitcnt lgkmcnt(0)
	v_mfma_f32_16x16x32_bf16 v[154:157], v[16:19], v[114:117], v[20:23]
	ds_read_b128 v[16:19], v146 offset:9408
	v_mfma_f32_16x16x32_bf16 v[24:27], v[24:27], v[118:121], 0
	s_waitcnt lgkmcnt(0)
	v_mfma_f32_16x16x32_bf16 v[150:153], v[16:19], v[114:117], v[24:27]
	ds_read_b128 v[16:19], v146 offset:14016
	v_mfma_f32_16x16x32_bf16 v[28:31], v[28:31], v[118:121], 0
	s_waitcnt lgkmcnt(0)
	v_mfma_f32_16x16x32_bf16 v[146:149], v[16:19], v[114:117], v[28:31]
	s_and_saveexec_b64 s[8:9], s[6:7]
	s_xor_b64 s[8:9], exec, s[8:9]
	s_cbranch_execnz .LBB0_1806
	s_andn2_saveexec_b64 s[8:9], s[8:9]
	s_cbranch_execnz .LBB0_1807

; template <int NC, int DQK, int DV, bool CAUSAL, bool PF> ...
;     ...
;     _Pragma("unroll") for (int c = 0; c < NC; ++c) {
;       f32x4 s[4];
;       _Pragma("unroll") for (int m = 0; m < 4; ++m) s[m] = f32x4{0.f, 0.f, 0.f, 0.f};
;       _Pragma("unroll") for (int ks = 0; ks < NKS; ++ks) _Pragma("unroll") for (int m = 0; m < 4; ++m) {
;         bf16x8 a = *(const bf16x8*)&Kb[(16 * m + fr) * KLD + c * DQK + ks * 32 + fq * 8];
;         s[m] = __builtin_amdgcn_mfma_f32_16x16x32_bf16(a, qf[c][ks], s[m], 0, 0, 0);
;       }
;       constexpr float THR = 8.f;
;       float tnew, psum = 0.f;
;       if (general) {
;         float tmax = -1e30f;
;         _Pragma("unroll") for (int m = 0; m < 4; ++m) _Pragma("unroll") for (int j = 0; j < 4; ++j) {
;           float v = s[m][j] * scale_log2 + bv[m][j];
;           s[m][j] = v; tmax = fmaxf(tmax, v);
;         }
;         tnew = tmax;
;       } else {
;         float rmax = fmaxf(fmaxf(s[0][0], s[0][1]), fmaxf(s[0][2], s[0][3]));
;         _Pragma("unroll") for (int m = 1; m < 4; ++m) rmax = fmaxf(rmax, fmaxf(fmaxf(s[m][0], s[m][1]), fmaxf(s[m][2], s[m][3])));
;         tnew = rmax * scale_log2 + bb;
;       }
;       if (__builtin_amdgcn_ballot_w64(tnew - mrun[c] > THR) != 0ull) {
;         tnew = fmaxf(tnew, sx<16>(tnew, lane)); tnew = fmaxf(tnew, sx<32>(tnew, lane));
;         float mnew = fmaxf(mrun[c], tnew);
;         float alpha = __builtin_amdgcn_exp2f(mrun[c] - mnew);
;         mrun[c] = mnew; lsum[c] *= alpha;
;         _Pragma("unroll") for (int v = 0; v < NVT; ++v) _Pragma("unroll") for (int j = 0; j < 4; ++j) O[c][v][j] *= alpha;
;       }
;       if (general) {
;         float mm = mrun[c];
;         _Pragma("unroll") for (int m = 0; m < 4; ++m) _Pragma("unroll") for (int j = 0; j < 4; ++j) { float pv = __builtin_amdgcn_exp2f(s[m][j] - mm); s[m][j] = pv; psum += pv; }
;       } else {
;         float cc = bb - mrun[c];
;         _Pragma("unroll") for (int m = 0; m < 4; ++m) _Pragma("unroll") for (int j = 0; j < 4; ++j) { float pv = __builtin_amdgcn_exp2f(s[m][j] * scale_log2 + cc); s[m][j] = pv; psum += pv; }
;       }
;       lsum[c] += psum;
;       _Pragma("unroll") for (int k2 = 0; k2 < 2; ++k2) {
;         uint2 lo = pack4(s[2 * k2][0], s[2 * k2][1], s[2 * k2][2], s[2 * k2][3]);
;         uint2 hi = pack4(s[2 * k2 + 1][0], s[2 * k2 + 1][1], s[2 * k2 + 1][2], s[2 * k2 + 1][3]);
.Lda_fast:
	v_add3_u32 v172, s38, v32, v195
	v_add3_u32 v173, s37, v32, v193
	ds_read_b128 v[146:149], v172
	ds_read_b128 v[150:153], v172 offset:4608
	ds_read_b128 v[154:157], v172 offset:9216
	ds_read_b128 v[158:161], v172 offset:13824
	ds_read_b128 v[16:19], v172 offset:64
	ds_read_b128 v[20:23], v172 offset:4672
	ds_read_b128 v[24:27], v172 offset:9280
	ds_read_b128 v[28:31], v172 offset:13888
	ds_read_b128 v[0:3], v172 offset:128
	ds_read_b128 v[4:7], v172 offset:4736
	ds_read_b128 v[8:11], v172 offset:9344
	ds_read_b128 v[12:15], v172 offset:13952
	s_waitcnt lgkmcnt(10)
	v_mfma_f32_16x16x32_bf16 v[146:149], v[146:149], v[138:141], 0
	v_mfma_f32_16x16x32_bf16 v[150:153], v[150:153], v[138:141], 0
	s_waitcnt lgkmcnt(8)
	v_mfma_f32_16x16x32_bf16 v[154:157], v[154:157], v[138:141], 0
	v_mfma_f32_16x16x32_bf16 v[158:161], v[158:161], v[138:141], 0
	s_waitcnt lgkmcnt(4)
	v_mfma_f32_16x16x32_bf16 v[146:149], v[16:19], v[134:137], v[146:149]
	v_mfma_f32_16x16x32_bf16 v[150:153], v[20:23], v[134:137], v[150:153]
	v_mfma_f32_16x16x32_bf16 v[154:157], v[24:27], v[134:137], v[154:157]
	v_mfma_f32_16x16x32_bf16 v[158:161], v[28:31], v[134:137], v[158:161]
	ds_read_b128 v[16:19], v172 offset:192
	ds_read_b128 v[20:23], v172 offset:4800
	ds_read_b128 v[24:27], v172 offset:9408
	ds_read_b128 v[28:31], v172 offset:14016
	ds_read_b128 v[122:125], v173 offset:36864
	ds_read_b128 v[126:129], v173 offset:39424
	ds_read_b128 v[130:133], v173 offset:41984
	ds_read_b128 v[142:145], v173 offset:44544
	s_waitcnt lgkmcnt(8)
	v_mfma_f32_16x16x32_bf16 v[0:3], v[0:3], v[118:121], 0
	v_mfma_f32_16x16x32_bf16 v[4:7], v[4:7], v[118:121], 0
	v_mfma_f32_16x16x32_bf16 v[8:11], v[8:11], v[118:121], 0
	v_mfma_f32_16x16x32_bf16 v[12:15], v[12:15], v[118:121], 0
	v_max3_f32 v174, v146, v147, v148
	v_max3_f32 v175, v149, v150, v151
	v_max3_f32 v174, v174, v152, v153
	v_max3_f32 v175, v175, v154, v155
	v_max3_f32 v174, v174, v156, v157
	v_max3_f32 v175, v175, v158, v159
	v_max3_f32 v174, v174, v160, v161
	v_max_f32_e32 v174, v174, v175
	v_fmamk_f32 v174, v174, 0x3e38aa3b, v170
	v_sub_f32_e32 v175, v174, v194
	v_cmp_lt_f32_e32 vcc, s33, v175
	s_cbranch_vccnz .Lda_resc0
.Lda_resc0_ret:
	v_sub_f32_e32 v175, v170, v194
	s_waitcnt lgkmcnt(4)
	v_mfma_f32_16x16x32_bf16 v[0:3], v[16:19], v[114:117], v[0:3]
	v_mfma_f32_16x16x32_bf16 v[4:7], v[20:23], v[114:117], v[4:7]
	v_mfma_f32_16x16x32_bf16 v[8:11], v[24:27], v[114:117], v[8:11]
	v_mfma_f32_16x16x32_bf16 v[12:15], v[28:31], v[114:117], v[12:15]
	ds_read_b128 v[16:19], v173 offset:47104
	ds_read_b128 v[20:23], v173 offset:49664
	ds_read_b128 v[24:27], v173 offset:52224
	ds_read_b128 v[28:31], v173 offset:54784
	v_fmamk_f32 v146, v146, 0x3e38aa3b, v175
	v_fmamk_f32 v147, v147, 0x3e38aa3b, v175
	v_fmamk_f32 v148, v148, 0x3e38aa3b, v175
	v_fmamk_f32 v149, v149, 0x3e38aa3b, v175
	v_fmamk_f32 v150, v150, 0x3e38aa3b, v175
	v_fmamk_f32 v151, v151, 0x3e38aa3b, v175
	v_fmamk_f32 v152, v152, 0x3e38aa3b, v175
	v_fmamk_f32 v153, v153, 0x3e38aa3b, v175
	v_fmamk_f32 v154, v154, 0x3e38aa3b, v175
	v_fmamk_f32 v155, v155, 0x3e38aa3b, v175
	v_fmamk_f32 v156, v156, 0x3e38aa3b, v175
	v_fmamk_f32 v157, v157, 0x3e38aa3b, v175
	v_fmamk_f32 v158, v158, 0x3e38aa3b, v175
	v_fmamk_f32 v159, v159, 0x3e38aa3b, v175
	v_fmamk_f32 v160, v160, 0x3e38aa3b, v175
	v_fmamk_f32 v161, v161, 0x3e38aa3b, v175
	v_exp_f32_e32 v146, v146
	v_exp_f32_e32 v147, v147
	v_exp_f32_e32 v148, v148
	v_add_f32_e32 v174, v147, v146
	v_exp_f32_e32 v149, v149
	v_add_f32_e32 v174, v148, v174
	v_exp_f32_e32 v150, v150
	v_add_f32_e32 v174, v149, v174
	v_exp_f32_e32 v151, v151
	v_add_f32_e32 v174, v150, v174
	v_exp_f32_e32 v152, v152
	v_add_f32_e32 v174, v151, v174
	v_exp_f32_e32 v153, v153
	v_add_f32_e32 v174, v152, v174
	v_exp_f32_e32 v154, v154
	v_add_f32_e32 v174, v153, v174
	v_exp_f32_e32 v155, v155
	v_add_f32_e32 v174, v154, v174
	v_exp_f32_e32 v156, v156
	v_add_f32_e32 v174, v155, v174
	v_exp_f32_e32 v157, v157
	v_add_f32_e32 v174, v156, v174
	v_exp_f32_e32 v158, v158
	v_add_f32_e32 v174, v157, v174
	v_exp_f32_e32 v159, v159
	v_add_f32_e32 v174, v158, v174
	v_exp_f32_e32 v160, v160
	v_add_f32_e32 v174, v159, v174
	v_exp_f32_e32 v161, v161
	v_add_f32_e32 v174, v160, v174
	v_cvt_pk_bf16_f32 v146, v146, v147
	v_add_f32_e32 v174, v161, v174
	v_cvt_pk_bf16_f32 v147, v148, v149
	v_add_f32_e32 v192, v192, v174
	v_cvt_pk_bf16_f32 v148, v150, v151
	v_cvt_pk_bf16_f32 v149, v152, v153
	v_cvt_pk_bf16_f32 v150, v154, v155
	v_cvt_pk_bf16_f32 v151, v156, v157
	v_cvt_pk_bf16_f32 v152, v158, v159
	v_cvt_pk_bf16_f32 v153, v160, v161
	ds_read_b128 v[154:157], v173 offset:36928
	ds_read_b128 v[158:161], v173 offset:39488
	v_max3_f32 v174, v0, v1, v2
	v_max3_f32 v175, v3, v4, v5
	v_max3_f32 v174, v174, v6, v7
	v_max3_f32 v175, v175, v8, v9
	v_max3_f32 v174, v174, v10, v11
	v_max3_f32 v175, v175, v12, v13
	v_max3_f32 v174, v174, v14, v15
	v_max_f32_e32 v174, v174, v175
	v_fmamk_f32 v174, v174, 0x3e38aa3b, v170
	v_sub_f32_e32 v175, v174, v171
	v_cmp_lt_f32_e32 vcc, s33, v175
	s_cbranch_vccnz .Lda_resc1
; __device__ __forceinline__ uint2 pack4(float a, float b, float c, float d) { uint2 r; r.x = pk2(a, b); r.y = pk2(c, d); return r; }
; template <int NC, int DQK, int DV, bool CAUSAL, bool PF> ...
;     ...
;         float cc = bb - mrun[c];
;         _Pragma("unroll") for (int m = 0; m < 4; ++m) _Pragma("unroll") for (int j = 0; j < 4; ++j) { float pv = __builtin_amdgcn_exp2f(s[m][j] * scale_log2 + cc); s[m][j] = pv; psum += pv; }
;       }
;       lsum[c] += psum;
;       _Pragma("unroll") for (int k2 = 0; k2 < 2; ++k2) {
;         uint2 lo = pack4(s[2 * k2][0], s[2 * k2][1], s[2 * k2][2], s[2 * k2][3]);
;         uint2 hi = pack4(s[2 * k2 + 1][0], s[2 * k2 + 1][1], s[2 * k2 + 1][2], s[2 * k2 + 1][3]);
;         uint4 pk; pk.x = lo.x; pk.y = lo.y; pk.z = hi.x; pk.w = hi.y;
;         pf[c][k2] = *(bf16x8*)&pk;
;       }
;     }
;     _Pragma("unroll") for (int k2 = 0; k2 < 2; ++k2) _Pragma("unroll") for (int v = 0; v < NVT; ++v) {
;       bf16x8 a = *(const bf16x8*)&Vb[(16 * v + fr) * VLD + 32 * k2 + fq * 8];
;       _Pragma("unroll") for (int c = 0; c < NC; ++c) O[c][v] = __builtin_amdgcn_mfma_f32_16x16x32_bf16(a, pf[c][k2], O[c][v], 0, 0, 0);
;       if ((v & 3) == 3) __builtin_amdgcn_sched_barrier(0);
;     }
.Lda_resc1_ret:
	v_sub_f32_e32 v175, v170, v171
	v_fmamk_f32 v0, v0, 0x3e38aa3b, v175
	v_fmamk_f32 v1, v1, 0x3e38aa3b, v175
	v_fmamk_f32 v2, v2, 0x3e38aa3b, v175
	v_fmamk_f32 v3, v3, 0x3e38aa3b, v175
	v_fmamk_f32 v4, v4, 0x3e38aa3b, v175
	v_fmamk_f32 v5, v5, 0x3e38aa3b, v175
	v_fmamk_f32 v6, v6, 0x3e38aa3b, v175
	v_fmamk_f32 v7, v7, 0x3e38aa3b, v175
	v_fmamk_f32 v8, v8, 0x3e38aa3b, v175
	v_fmamk_f32 v9, v9, 0x3e38aa3b, v175
	v_fmamk_f32 v10, v10, 0x3e38aa3b, v175
	v_fmamk_f32 v11, v11, 0x3e38aa3b, v175
	v_fmamk_f32 v12, v12, 0x3e38aa3b, v175
	v_fmamk_f32 v13, v13, 0x3e38aa3b, v175
	v_fmamk_f32 v14, v14, 0x3e38aa3b, v175
	v_fmamk_f32 v15, v15, 0x3e38aa3b, v175
	v_exp_f32_e32 v0, v0
	v_exp_f32_e32 v1, v1
	v_exp_f32_e32 v2, v2
	v_add_f32_e32 v174, v1, v0
	v_exp_f32_e32 v3, v3
	v_add_f32_e32 v174, v2, v174
	v_exp_f32_e32 v4, v4
	v_add_f32_e32 v174, v3, v174
	v_exp_f32_e32 v5, v5
	v_add_f32_e32 v174, v4, v174
	v_exp_f32_e32 v6, v6
	v_add_f32_e32 v174, v5, v174
	v_exp_f32_e32 v7, v7
	v_add_f32_e32 v174, v6, v174
	v_exp_f32_e32 v8, v8
	v_add_f32_e32 v174, v7, v174
	v_exp_f32_e32 v9, v9
	v_add_f32_e32 v174, v8, v174
	v_exp_f32_e32 v10, v10
	v_add_f32_e32 v174, v9, v174
	v_exp_f32_e32 v11, v11
	v_add_f32_e32 v174, v10, v174
	v_exp_f32_e32 v12, v12
	v_add_f32_e32 v174, v11, v174
	v_exp_f32_e32 v13, v13
	v_add_f32_e32 v174, v12, v174
	v_exp_f32_e32 v14, v14
	v_add_f32_e32 v174, v13, v174
	v_exp_f32_e32 v15, v15
	v_add_f32_e32 v174, v14, v174
	v_cvt_pk_bf16_f32 v0, v0, v1
	v_add_f32_e32 v174, v15, v174
	v_cvt_pk_bf16_f32 v1, v2, v3
	v_add_f32_e32 v191, v191, v174
	v_cvt_pk_bf16_f32 v2, v4, v5
	v_cvt_pk_bf16_f32 v3, v6, v7
	v_cvt_pk_bf16_f32 v4, v8, v9
	v_cvt_pk_bf16_f32 v5, v10, v11
	v_cvt_pk_bf16_f32 v6, v12, v13
	v_cvt_pk_bf16_f32 v7, v14, v15
	ds_read_b128 v[8:11], v173 offset:42048
	ds_read_b128 v[12:15], v173 offset:44608
	s_waitcnt lgkmcnt(10)
	v_mfma_f32_16x16x32_bf16 v[106:109], v[122:125], v[146:149], v[106:109]
	v_mfma_f32_16x16x32_bf16 v[110:113], v[122:125], v[0:3], v[110:113]
	v_mfma_f32_16x16x32_bf16 v[98:101], v[126:129], v[146:149], v[98:101]
	v_mfma_f32_16x16x32_bf16 v[102:105], v[126:129], v[0:3], v[102:105]
	s_waitcnt lgkmcnt(8)
	v_mfma_f32_16x16x32_bf16 v[90:93], v[130:133], v[146:149], v[90:93]
	v_mfma_f32_16x16x32_bf16 v[94:97], v[130:133], v[0:3], v[94:97]
	v_mfma_f32_16x16x32_bf16 v[78:81], v[142:145], v[146:149], v[78:81]
	v_mfma_f32_16x16x32_bf16 v[74:77], v[142:145], v[0:3], v[74:77]
	ds_read_b128 v[122:125], v173 offset:47168
	ds_read_b128 v[126:129], v173 offset:49728
	ds_read_b128 v[130:133], v173 offset:52288
	ds_read_b128 v[142:145], v173 offset:54848
	s_waitcnt lgkmcnt(10)
	v_mfma_f32_16x16x32_bf16 v[62:65], v[16:19], v[146:149], v[62:65]
	v_mfma_f32_16x16x32_bf16 v[70:73], v[16:19], v[0:3], v[70:73]
	v_mfma_f32_16x16x32_bf16 v[50:53], v[20:23], v[146:149], v[50:53]
	v_mfma_f32_16x16x32_bf16 v[66:69], v[20:23], v[0:3], v[66:69]
	s_waitcnt lgkmcnt(8)
	v_mfma_f32_16x16x32_bf16 v[54:57], v[24:27], v[146:149], v[54:57]
	v_mfma_f32_16x16x32_bf16 v[58:61], v[24:27], v[0:3], v[58:61]
	v_mfma_f32_16x16x32_bf16 v[82:85], v[28:31], v[146:149], v[82:85]
	v_mfma_f32_16x16x32_bf16 v[86:89], v[28:31], v[0:3], v[86:89]
	s_waitcnt lgkmcnt(6)
	v_mfma_f32_16x16x32_bf16 v[106:109], v[154:157], v[150:153], v[106:109]
	v_mfma_f32_16x16x32_bf16 v[110:113], v[154:157], v[4:7], v[110:113]
	v_mfma_f32_16x16x32_bf16 v[98:101], v[158:161], v[150:153], v[98:101]
	v_mfma_f32_16x16x32_bf16 v[102:105], v[158:161], v[4:7], v[102:105]
	s_waitcnt lgkmcnt(4)
	v_mfma_f32_16x16x32_bf16 v[90:93], v[8:11], v[150:153], v[90:93]
	v_mfma_f32_16x16x32_bf16 v[94:97], v[8:11], v[4:7], v[94:97]
	v_mfma_f32_16x16x32_bf16 v[78:81], v[12:15], v[150:153], v[78:81]
	v_mfma_f32_16x16x32_bf16 v[74:77], v[12:15], v[4:7], v[74:77]
	s_waitcnt lgkmcnt(2)
	v_mfma_f32_16x16x32_bf16 v[62:65], v[122:125], v[150:153], v[62:65]
	v_mfma_f32_16x16x32_bf16 v[70:73], v[122:125], v[4:7], v[70:73]
	v_mfma_f32_16x16x32_bf16 v[50:53], v[126:129], v[150:153], v[50:53]
	v_mfma_f32_16x16x32_bf16 v[66:69], v[126:129], v[4:7], v[66:69]
	s_waitcnt lgkmcnt(0)
	v_mfma_f32_16x16x32_bf16 v[54:57], v[130:133], v[150:153], v[54:57]
	v_mfma_f32_16x16x32_bf16 v[58:61], v[130:133], v[4:7], v[58:61]
	v_mfma_f32_16x16x32_bf16 v[82:85], v[142:145], v[150:153], v[82:85]
	v_mfma_f32_16x16x32_bf16 v[86:89], v[142:145], v[4:7], v[86:89]
	s_branch .LBB0_1784

; template <int NC, int DQK, int DV, bool CAUSAL, bool PF> ...
;     ...
;     _Pragma("unroll") for (int c = 0; c < NC; ++c) {
;       f32x4 s[4];
;       _Pragma("unroll") for (int m = 0; m < 4; ++m) s[m] = f32x4{0.f, 0.f, 0.f, 0.f};
;       _Pragma("unroll") for (int ks = 0; ks < NKS; ++ks) _Pragma("unroll") for (int m = 0; m < 4; ++m) {
;         bf16x8 a = *(const bf16x8*)&Kb[(16 * m + fr) * KLD + c * DQK + ks * 32 + fq * 8];
;         s[m] = __builtin_amdgcn_mfma_f32_16x16x32_bf16(a, qf[c][ks], s[m], 0, 0, 0);
;       }
;       constexpr float THR = 8.f;
;       float tnew, psum = 0.f;
;       if (general) {
;         float tmax = -1e30f;
;         _Pragma("unroll") for (int m = 0; m < 4; ++m) _Pragma("unroll") for (int j = 0; j < 4; ++j) {
;           float v = s[m][j] * scale_log2 + bv[m][j];
;           s[m][j] = v; tmax = fmaxf(tmax, v);
;         }
;         tnew = tmax;
;       } else {
;         float rmax = fmaxf(fmaxf(s[0][0], s[0][1]), fmaxf(s[0][2], s[0][3]));
;         _Pragma("unroll") for (int m = 1; m < 4; ++m) rmax = fmaxf(rmax, fmaxf(fmaxf(s[m][0], s[m][1]), fmaxf(s[m][2], s[m][3])));
;         tnew = rmax * scale_log2 + bb;
;       }
;       if (__builtin_amdgcn_ballot_w64(tnew - mrun[c] > THR) != 0ull) {
;         tnew = fmaxf(tnew, sx<16>(tnew, lane)); tnew = fmaxf(tnew, sx<32>(tnew, lane));
;         float mnew = fmaxf(mrun[c], tnew);
;         float alpha = __builtin_amdgcn_exp2f(mrun[c] - mnew);
;         mrun[c] = mnew; lsum[c] *= alpha;
;         _Pragma("unroll") for (int v = 0; v < NVT; ++v) _Pragma("unroll") for (int j = 0; j < 4; ++j) O[c][v][j] *= alpha;
;       }
;       if (general) {
;         float mm = mrun[c];
;         _Pragma("unroll") for (int m = 0; m < 4; ++m) _Pragma("unroll") for (int j = 0; j < 4; ++j) { float pv = __builtin_amdgcn_exp2f(s[m][j] - mm); s[m][j] = pv; psum += pv; }
;       } else {
;         float cc = bb - mrun[c];
;         _Pragma("unroll") for (int m = 0; m < 4; ++m) _Pragma("unroll") for (int j = 0; j < 4; ++j) { float pv = __builtin_amdgcn_exp2f(s[m][j] * scale_log2 + cc); s[m][j] = pv; psum += pv; }
;       }
;       lsum[c] += psum;
;       _Pragma("unroll") for (int k2 = 0; k2 < 2; ++k2) {
;         uint2 lo = pack4(s[2 * k2][0], s[2 * k2][1], s[2 * k2][2], s[2 * k2][3]);
;         uint2 hi = pack4(s[2 * k2 + 1][0], s[2 * k2 + 1][1], s[2 * k2 + 1][2], s[2 * k2 + 1][3]);
.Ldb_fastB:
	v_add3_u32 v172, s38, v32, v195
	s_cmp_eq_u32 s34, 0
	s_cbranch_scc1 .Ldb_B_nopend
	s_sub_i32 s8, s37, 0x5000
	s_cmp_lt_i32 s8, 0
	s_cselect_b32 s8, 0xa000, s8
	v_add3_u32 v173, s8, v32, v193
	ds_read_b128 v[0:3], v173 offset:36864
	ds_read_b128 v[4:7], v173 offset:39424
	ds_read_b128 v[8:11], v173 offset:41984
	ds_read_b128 v[12:15], v173 offset:44544
	ds_read_b128 v[16:19], v173 offset:47104
	ds_read_b128 v[20:23], v173 offset:49664
	ds_read_b128 v[24:27], v173 offset:52224
	ds_read_b128 v[28:31], v173 offset:54784
	ds_read_b128 v[122:125], v173 offset:36928
	ds_read_b128 v[126:129], v173 offset:39488
	ds_read_b128 v[130:133], v173 offset:42048
	ds_read_b128 v[142:145], v173 offset:44608
	s_waitcnt lgkmcnt(10)
	v_mfma_f32_16x16x32_bf16 v[106:109], v[0:3], v[146:149], v[106:109]
	v_mfma_f32_16x16x32_bf16 v[110:113], v[0:3], v[154:157], v[110:113]
	v_mfma_f32_16x16x32_bf16 v[98:101], v[4:7], v[146:149], v[98:101]
	v_mfma_f32_16x16x32_bf16 v[102:105], v[4:7], v[154:157], v[102:105]
	s_waitcnt lgkmcnt(8)
	v_mfma_f32_16x16x32_bf16 v[90:93], v[8:11], v[146:149], v[90:93]
	v_mfma_f32_16x16x32_bf16 v[94:97], v[8:11], v[154:157], v[94:97]
	v_mfma_f32_16x16x32_bf16 v[78:81], v[12:15], v[146:149], v[78:81]
	v_mfma_f32_16x16x32_bf16 v[74:77], v[12:15], v[154:157], v[74:77]
	ds_read_b128 v[0:3], v173 offset:47168
	ds_read_b128 v[4:7], v173 offset:49728
	ds_read_b128 v[8:11], v173 offset:52288
	ds_read_b128 v[12:15], v173 offset:54848
	s_waitcnt lgkmcnt(10)
	v_mfma_f32_16x16x32_bf16 v[62:65], v[16:19], v[146:149], v[62:65]
	v_mfma_f32_16x16x32_bf16 v[70:73], v[16:19], v[154:157], v[70:73]
	v_mfma_f32_16x16x32_bf16 v[50:53], v[20:23], v[146:149], v[50:53]
	v_mfma_f32_16x16x32_bf16 v[66:69], v[20:23], v[154:157], v[66:69]
	s_waitcnt lgkmcnt(8)
	v_mfma_f32_16x16x32_bf16 v[54:57], v[24:27], v[146:149], v[54:57]
	v_mfma_f32_16x16x32_bf16 v[58:61], v[24:27], v[154:157], v[58:61]
	v_mfma_f32_16x16x32_bf16 v[82:85], v[28:31], v[146:149], v[82:85]
	v_mfma_f32_16x16x32_bf16 v[86:89], v[28:31], v[154:157], v[86:89]
	ds_read_b128 v[16:19], v172 offset:64
	ds_read_b128 v[20:23], v172 offset:4672
	ds_read_b128 v[24:27], v172 offset:9280
	ds_read_b128 v[28:31], v172 offset:13888
	s_waitcnt lgkmcnt(10)
	v_mfma_f32_16x16x32_bf16 v[106:109], v[122:125], v[150:153], v[106:109]
	v_mfma_f32_16x16x32_bf16 v[110:113], v[122:125], v[158:161], v[110:113]
	v_mfma_f32_16x16x32_bf16 v[98:101], v[126:129], v[150:153], v[98:101]
	v_mfma_f32_16x16x32_bf16 v[102:105], v[126:129], v[158:161], v[102:105]
	s_waitcnt lgkmcnt(8)
	v_mfma_f32_16x16x32_bf16 v[90:93], v[130:133], v[150:153], v[90:93]
	v_mfma_f32_16x16x32_bf16 v[94:97], v[130:133], v[158:161], v[94:97]
	v_mfma_f32_16x16x32_bf16 v[78:81], v[142:145], v[150:153], v[78:81]
	v_mfma_f32_16x16x32_bf16 v[74:77], v[142:145], v[158:161], v[74:77]
	ds_read_b128 v[122:125], v172
	ds_read_b128 v[126:129], v172 offset:4608
	ds_read_b128 v[130:133], v172 offset:9216
	ds_read_b128 v[142:145], v172 offset:13824
	s_waitcnt lgkmcnt(10)
	v_mfma_f32_16x16x32_bf16 v[62:65], v[0:3], v[150:153], v[62:65]
	v_mfma_f32_16x16x32_bf16 v[70:73], v[0:3], v[158:161], v[70:73]
	v_mfma_f32_16x16x32_bf16 v[50:53], v[4:7], v[150:153], v[50:53]
	v_mfma_f32_16x16x32_bf16 v[66:69], v[4:7], v[158:161], v[66:69]
	s_waitcnt lgkmcnt(8)
	v_mfma_f32_16x16x32_bf16 v[54:57], v[8:11], v[150:153], v[54:57]
	v_mfma_f32_16x16x32_bf16 v[58:61], v[8:11], v[158:161], v[58:61]
	v_mfma_f32_16x16x32_bf16 v[82:85], v[12:15], v[150:153], v[82:85]
	v_mfma_f32_16x16x32_bf16 v[86:89], v[12:15], v[158:161], v[86:89]
	ds_read_b128 v[0:3], v172 offset:128
	ds_read_b128 v[4:7], v172 offset:4736
	ds_read_b128 v[8:11], v172 offset:9344
	ds_read_b128 v[12:15], v172 offset:13952
	s_branch .Ldb_B_qk
.Ldb_B_nopend:
	ds_read_b128 v[16:19], v172 offset:64
	ds_read_b128 v[20:23], v172 offset:4672
	ds_read_b128 v[24:27], v172 offset:9280
	ds_read_b128 v[28:31], v172 offset:13888
	ds_read_b128 v[122:125], v172
	ds_read_b128 v[126:129], v172 offset:4608
	ds_read_b128 v[130:133], v172 offset:9216
	ds_read_b128 v[142:145], v172 offset:13824
	ds_read_b128 v[0:3], v172 offset:128
	ds_read_b128 v[4:7], v172 offset:4736
	ds_read_b128 v[8:11], v172 offset:9344
	ds_read_b128 v[12:15], v172 offset:13952
.Ldb_B_qk:
	s_waitcnt lgkmcnt(4)
	v_mfma_f32_16x16x32_bf16 v[122:125], v[122:125], v[138:141], 0
	v_mfma_f32_16x16x32_bf16 v[126:129], v[126:129], v[138:141], 0
	v_mfma_f32_16x16x32_bf16 v[130:133], v[130:133], v[138:141], 0
	v_mfma_f32_16x16x32_bf16 v[142:145], v[142:145], v[138:141], 0
	v_mfma_f32_16x16x32_bf16 v[122:125], v[16:19], v[134:137], v[122:125]
	v_mfma_f32_16x16x32_bf16 v[126:129], v[20:23], v[134:137], v[126:129]
	v_mfma_f32_16x16x32_bf16 v[130:133], v[24:27], v[134:137], v[130:133]
	v_mfma_f32_16x16x32_bf16 v[142:145], v[28:31], v[134:137], v[142:145]
	ds_read_b128 v[16:19], v172 offset:192
	ds_read_b128 v[20:23], v172 offset:4800
	ds_read_b128 v[24:27], v172 offset:9408
	ds_read_b128 v[28:31], v172 offset:14016
	s_waitcnt lgkmcnt(4)
	v_mfma_f32_16x16x32_bf16 v[0:3], v[0:3], v[118:121], 0
	v_mfma_f32_16x16x32_bf16 v[4:7], v[4:7], v[118:121], 0
	v_mfma_f32_16x16x32_bf16 v[8:11], v[8:11], v[118:121], 0
	v_mfma_f32_16x16x32_bf16 v[12:15], v[12:15], v[118:121], 0
	v_max3_f32 v174, v122, v123, v124
	v_max3_f32 v175, v125, v126, v127
	v_max3_f32 v174, v174, v128, v129
	v_max3_f32 v175, v175, v130, v131
	v_max3_f32 v174, v174, v132, v133
	v_max3_f32 v175, v175, v142, v143
	v_max3_f32 v174, v174, v144, v145
	v_max_f32_e32 v174, v174, v175
	v_fmamk_f32 v174, v174, 0x3e38aa3b, v170
	v_sub_f32_e32 v175, v174, v194
	v_cmp_lt_f32_e32 vcc, s33, v175
	s_cbranch_vccnz .Ldb_resc0

; #define FA_PREFETCH(kt_) do { int k0_ = (kt_) * 64; \
;     _Pragma("unroll") for (int i = 0; i < KPT; ++i) kreg[i] = __builtin_amdgcn_raw_buffer_load_b128(rsK, kvo[i], k0_ * k_stride * 2, 0); \
;     _Pragma("unroll") for (int i = 0; i < VPT; ++i) vreg[i] = __builtin_amdgcn_raw_buffer_load_b128(rsV, vvo[i], k0_ * 2, 0); } while (0)
; #define FA_PREFETCH_NEXT() do { \
;     _Pragma("unroll") for (int i = 0; i < KPT; ++i) kreg[i] = __builtin_amdgcn_raw_buffer_load_b128(rsNK, kvo[i], 0, 0); \
;     _Pragma("unroll") for (int i = 0; i < VPT; ++i) vreg[i] = __builtin_amdgcn_raw_buffer_load_b128(rsNV, vvo[i], 0, 0); } while (0)
; template <int NC, int DQK, int DV, bool CAUSAL, bool PF> ...
;     ...
;   for (int kt = 0; kt < nkt; ++kt) {
;     if (!PF) FA_PREFETCH(kt);
;     u16* Kb = Ks + (kt & 1) * KBUF; u16* Vb = Vs + (kt & 1) * VBUF;
;     _Pragma("unroll") for (int i = 0; i < KPT; ++i) { int id = tid + i * 512, row = id / KCH, cc = id % KCH; *(u32x4*)&Kb[row * KLD + cc * 8] = kreg[i]; }
;     _Pragma("unroll") for (int i = 0; i < VPT; ++i) {
;       int id = tid + i * 512, row = id >> 3, cc = id & 7;
;       int pos = 32 * (cc >> 2) + 16 * (cc & 1) + 4 * ((cc >> 1) & 1);
;       uint2 lo2, hi2; lo2.x = vreg[i][0]; lo2.y = vreg[i][1]; hi2.x = vreg[i][2]; hi2.y = vreg[i][3];
;       *(uint2*)&Vb[row * VLD + pos] = lo2; *(uint2*)&Vb[row * VLD + pos + 8] = hi2;
;     }
;     __syncthreads();
;     if (PF && kt + 1 < nkt) FA_PREFETCH(kt + 1); else if (PF && has_next_item) FA_PREFETCH_NEXT();
;     ...
;     _Pragma("unroll") for (int k2 = 0; k2 < 2; ++k2) _Pragma("unroll") for (int v = 0; v < NVT; ++v) {
;       bf16x8 a = *(const bf16x8*)&Vb[(16 * v + fr) * VLD + 32 * k2 + fq * 8];
;       _Pragma("unroll") for (int c = 0; c < NC; ++c) O[c][v] = __builtin_amdgcn_mfma_f32_16x16x32_bf16(a, pf[c][k2], O[c][v], 0, 0, 0);
;       if ((v & 3) == 3) __builtin_amdgcn_sched_barrier(0);
;     }
.Ldb_flushB:
	s_sub_i32 s8, s37, 0x5000
	s_cmp_lt_i32 s8, 0
	s_cselect_b32 s8, 0xa000, s8
	v_add3_u32 v173, s8, v32, v193
	ds_read_b128 v[0:3], v173 offset:36864
	ds_read_b128 v[4:7], v173 offset:39424
	ds_read_b128 v[8:11], v173 offset:41984
	ds_read_b128 v[12:15], v173 offset:44544
	ds_read_b128 v[16:19], v173 offset:47104
	ds_read_b128 v[20:23], v173 offset:49664
	ds_read_b128 v[24:27], v173 offset:52224
	ds_read_b128 v[28:31], v173 offset:54784
	ds_read_b128 v[122:125], v173 offset:36928
	ds_read_b128 v[126:129], v173 offset:39488
	ds_read_b128 v[130:133], v173 offset:42048
	ds_read_b128 v[142:145], v173 offset:44608
	s_waitcnt lgkmcnt(10)
	v_mfma_f32_16x16x32_bf16 v[106:109], v[0:3], v[146:149], v[106:109]
	v_mfma_f32_16x16x32_bf16 v[110:113], v[0:3], v[154:157], v[110:113]
	v_mfma_f32_16x16x32_bf16 v[98:101], v[4:7], v[146:149], v[98:101]
	v_mfma_f32_16x16x32_bf16 v[102:105], v[4:7], v[154:157], v[102:105]
	s_waitcnt lgkmcnt(8)
	v_mfma_f32_16x16x32_bf16 v[90:93], v[8:11], v[146:149], v[90:93]
	v_mfma_f32_16x16x32_bf16 v[94:97], v[8:11], v[154:157], v[94:97]
	v_mfma_f32_16x16x32_bf16 v[78:81], v[12:15], v[146:149], v[78:81]
	v_mfma_f32_16x16x32_bf16 v[74:77], v[12:15], v[154:157], v[74:77]
	ds_read_b128 v[0:3], v173 offset:47168
	ds_read_b128 v[4:7], v173 offset:49728
	ds_read_b128 v[8:11], v173 offset:52288
	ds_read_b128 v[12:15], v173 offset:54848
	s_waitcnt lgkmcnt(10)
	v_mfma_f32_16x16x32_bf16 v[62:65], v[16:19], v[146:149], v[62:65]
	v_mfma_f32_16x16x32_bf16 v[70:73], v[16:19], v[154:157], v[70:73]
	v_mfma_f32_16x16x32_bf16 v[50:53], v[20:23], v[146:149], v[50:53]
	v_mfma_f32_16x16x32_bf16 v[66:69], v[20:23], v[154:157], v[66:69]
	s_waitcnt lgkmcnt(8)
	v_mfma_f32_16x16x32_bf16 v[54:57], v[24:27], v[146:149], v[54:57]
	v_mfma_f32_16x16x32_bf16 v[58:61], v[24:27], v[154:157], v[58:61]
	v_mfma_f32_16x16x32_bf16 v[82:85], v[28:31], v[146:149], v[82:85]
	v_mfma_f32_16x16x32_bf16 v[86:89], v[28:31], v[154:157], v[86:89]
	s_waitcnt lgkmcnt(6)
	v_mfma_f32_16x16x32_bf16 v[106:109], v[122:125], v[150:153], v[106:109]
	v_mfma_f32_16x16x32_bf16 v[110:113], v[122:125], v[158:161], v[110:113]
	v_mfma_f32_16x16x32_bf16 v[98:101], v[126:129], v[150:153], v[98:101]
	v_mfma_f32_16x16x32_bf16 v[102:105], v[126:129], v[158:161], v[102:105]
	s_waitcnt lgkmcnt(4)
	v_mfma_f32_16x16x32_bf16 v[90:93], v[130:133], v[150:153], v[90:93]
	v_mfma_f32_16x16x32_bf16 v[94:97], v[130:133], v[158:161], v[94:97]
	v_mfma_f32_16x16x32_bf16 v[78:81], v[142:145], v[150:153], v[78:81]
	v_mfma_f32_16x16x32_bf16 v[74:77], v[142:145], v[158:161], v[74:77]
	s_waitcnt lgkmcnt(2)
	v_mfma_f32_16x16x32_bf16 v[62:65], v[0:3], v[150:153], v[62:65]
	v_mfma_f32_16x16x32_bf16 v[70:73], v[0:3], v[158:161], v[70:73]
	v_mfma_f32_16x16x32_bf16 v[50:53], v[4:7], v[150:153], v[50:53]
	v_mfma_f32_16x16x32_bf16 v[66:69], v[4:7], v[158:161], v[66:69]
	s_waitcnt lgkmcnt(0)
	v_mfma_f32_16x16x32_bf16 v[54:57], v[8:11], v[150:153], v[54:57]
	v_mfma_f32_16x16x32_bf16 v[58:61], v[8:11], v[158:161], v[58:61]
	v_mfma_f32_16x16x32_bf16 v[82:85], v[12:15], v[150:153], v[82:85]
	v_mfma_f32_16x16x32_bf16 v[86:89], v[12:15], v[158:161], v[86:89]
	v_cmp_gt_i32_e32 vcc, s35, v202
	s_branch .Lda_gen_cont
.LBB0_1808:
	s_add_i32 s28, s28, s70
	s_cmpk_gt_i32 s28, 0x7ff
	s_cselect_b64 s[12:13], -1, 0
	s_and_b32 s0, s30, 1
	s_mul_i32 s1, s0, 0x4800
	s_add_i32 s34, s1, 0
	v_add3_u32 v0, s34, v210, v204
	s_mul_hi_u32 s0, s30, 0xaaaaaaab
	s_lshr_b32 s0, s0, 1
	s_mul_i32 s0, s0, 3
	s_sub_i32 s0, s30, s0
	s_mul_i32 s0, s0, 0x5000
	s_waitcnt vmcnt(3)
	ds_write_b128 v0, v[34:37]
	v_add3_u32 v0, s34, v209, v205
	s_mov_b32 s31, s0
	s_waitcnt vmcnt(2)
	ds_write_b128 v0, v[38:41]
	v_lshl_add_u32 v0, v206, 1, s31
	v_add3_u32 v0, v0, v211, v212
	v_add_u32_e32 v1, v0, v208
	v_add_u32_e32 v0, v0, v207
	v_add_u32_e32 v1, 0x9000, v1
	v_add_u32_e32 v0, 0x9000, v0
	s_and_b64 vcc, exec, s[12:13]
	s_waitcnt vmcnt(0)
	ds_write2_b64 v1, v[42:43], v[44:45] offset1:2
	ds_write2_b64 v0, v[46:47], v[48:49] offset1:2
	s_waitcnt lgkmcnt(0)
	s_barrier
	s_cbranch_vccnz .LBB0_1810
	s_ashr_i32 s0, s28, 9
	s_ashr_i32 s1, s0, 31
	s_lshl_b64 s[6:7], s[0:1], 24
	s_add_u32 s1, s22, s6
	s_addc_u32 s6, s23, s7
	s_lshl_b32 s7, s28, 7
	s_and_b32 s7, s7, 0x380
	s_lshl_b32 s8, s7, 1
	s_add_u32 s80, s1, s8
	s_addc_u32 s6, s6, 0
	s_lshl_b32 s0, s0, 10
	s_or_b32 s0, s0, s7
	s_ashr_i32 s1, s0, 31
	s_lshl_b64 s[0:1], s[0:1], 14
	v_readlane_b32 s36, v254, 26
	v_readlane_b32 s39, v254, 29
	s_add_u32 s36, s24, s0
	v_readlane_b32 s37, v254, 27
	v_readlane_b32 s38, v254, 28
	s_addc_u32 s0, s25, s1
	s_and_b32 s81, s6, 0xffff
	s_mov_b32 s83, s39
	s_and_b32 s37, s0, 0xffff
	s_mov_b32 s38, s82
	buffer_load_dwordx4 v[34:37], v198, s[80:83], 0 offen
	buffer_load_dwordx4 v[38:41], v199, s[80:83], 0 offen
	buffer_load_dwordx4 v[42:45], v201, s[36:39], 0 offen
	buffer_load_dwordx4 v[46:49], v200, s[36:39], 0 offen
	s_mov_b32 s7, s39
	v_writelane_b32 v254, s4, 26
	s_nop 1
	v_writelane_b32 v254, s5, 27
	v_writelane_b32 v254, s6, 28
	v_writelane_b32 v254, s7, 29

; template <int NC, int DQK, int DV, bool CAUSAL, bool PF> ...
;     ...
;     _Pragma("unroll") for (int c = 0; c < NC; ++c) {
;       f32x4 s[4];
;       _Pragma("unroll") for (int m = 0; m < 4; ++m) s[m] = f32x4{0.f, 0.f, 0.f, 0.f};
;       _Pragma("unroll") for (int ks = 0; ks < NKS; ++ks) _Pragma("unroll") for (int m = 0; m < 4; ++m) {
;         bf16x8 a = *(const bf16x8*)&Kb[(16 * m + fr) * KLD + c * DQK + ks * 32 + fq * 8];
;         s[m] = __builtin_amdgcn_mfma_f32_16x16x32_bf16(a, qf[c][ks], s[m], 0, 0, 0);
;       }
.LBB0_1813:
	s_or_b64 exec, exec, s[14:15]
	v_add_u32_e32 v0, s34, v32
	v_add_u32_e32 v149, v0, v195
	ds_read_b128 v[0:3], v149
	ds_read_b128 v[16:19], v149 offset:64
	ds_read_b128 v[4:7], v149 offset:4608
	ds_read_b128 v[8:11], v149 offset:9216
	ds_read_b128 v[12:15], v149 offset:13824
	s_waitcnt lgkmcnt(4)
	v_mfma_f32_16x16x32_bf16 v[0:3], v[0:3], v[138:141], 0
	s_waitcnt lgkmcnt(3)
	v_mfma_f32_16x16x32_bf16 v[28:31], v[16:19], v[134:137], v[0:3]
	s_nop 5
	ds_read_b128 v[0:3], v149 offset:4672
	s_waitcnt lgkmcnt(3)
	v_mfma_f32_16x16x32_bf16 v[4:7], v[4:7], v[138:141], 0
	s_waitcnt lgkmcnt(0)
	v_mfma_f32_16x16x32_bf16 v[24:27], v[0:3], v[134:137], v[4:7]
	ds_read_b128 v[0:3], v149 offset:9280
	v_mfma_f32_16x16x32_bf16 v[8:11], v[8:11], v[138:141], 0
	s_waitcnt lgkmcnt(0)
	v_mfma_f32_16x16x32_bf16 v[20:23], v[0:3], v[134:137], v[8:11]
	ds_read_b128 v[0:3], v149 offset:13888
	v_mfma_f32_16x16x32_bf16 v[12:15], v[12:15], v[138:141], 0
	s_waitcnt lgkmcnt(0)
	v_mfma_f32_16x16x32_bf16 v[16:19], v[0:3], v[134:137], v[12:15]
	s_and_saveexec_b64 s[8:9], s[6:7]
	s_xor_b64 s[8:9], exec, s[8:9]
	s_cbranch_execnz .LBB0_1829
	s_andn2_saveexec_b64 s[8:9], s[8:9]
	s_cbranch_execnz .LBB0_1830

; template <int NC, int DQK, int DV, bool CAUSAL, bool PF> ...
;     ...
;       _Pragma("unroll") for (int ks = 0; ks < NKS; ++ks) _Pragma("unroll") for (int m = 0; m < 4; ++m) {
;         bf16x8 a = *(const bf16x8*)&Kb[(16 * m + fr) * KLD + c * DQK + ks * 32 + fq * 8];
;         s[m] = __builtin_amdgcn_mfma_f32_16x16x32_bf16(a, qf[c][ks], s[m], 0, 0, 0);
;       }
;       constexpr float THR = 8.f;
;       float tnew, psum = 0.f;
;       if (general) {
;         float tmax = -1e30f;
;         _Pragma("unroll") for (int m = 0; m < 4; ++m) _Pragma("unroll") for (int j = 0; j < 4; ++j) {
;           float v = s[m][j] * scale_log2 + bv[m][j];
.LBB0_1821:
	s_or_b64 exec, exec, s[8:9]
	ds_read_b128 v[16:19], v149 offset:128
	ds_read_b128 v[20:23], v149 offset:4736
	ds_read_b128 v[24:27], v149 offset:9344
	ds_read_b128 v[28:31], v149 offset:13952
	s_waitcnt lgkmcnt(3)
	v_mfma_f32_16x16x32_bf16 v[16:19], v[16:19], v[118:121], 0
	s_waitcnt lgkmcnt(2)
	v_mfma_f32_16x16x32_bf16 v[20:23], v[20:23], v[118:121], 0
	s_waitcnt lgkmcnt(1)
	v_mfma_f32_16x16x32_bf16 v[24:27], v[24:27], v[118:121], 0
	s_waitcnt lgkmcnt(0)
	v_mfma_f32_16x16x32_bf16 v[28:31], v[28:31], v[118:121], 0
	ds_read_b128 v[118:121], v149 offset:192
	s_waitcnt lgkmcnt(0)
	v_mfma_f32_16x16x32_bf16 v[138:141], v[118:121], v[114:117], v[16:19]
	s_nop 2
	ds_read_b128 v[16:19], v149 offset:4800
	s_waitcnt lgkmcnt(0)
	v_mfma_f32_16x16x32_bf16 v[134:137], v[16:19], v[114:117], v[20:23]
	ds_read_b128 v[16:19], v149 offset:9408
	s_waitcnt lgkmcnt(0)
	v_mfma_f32_16x16x32_bf16 v[118:121], v[16:19], v[114:117], v[24:27]
	ds_read_b128 v[16:19], v149 offset:14016
	s_waitcnt lgkmcnt(0)
	v_mfma_f32_16x16x32_bf16 v[114:117], v[16:19], v[114:117], v[28:31]
	s_and_saveexec_b64 s[8:9], s[6:7]
	s_xor_b64 s[8:9], exec, s[8:9]
	s_cbranch_execnz .LBB0_1831
	s_andn2_saveexec_b64 s[8:9], s[8:9]
	s_cbranch_execnz .LBB0_1832
